# speedup vs baseline: 1.0132x; 1.0003x over previous
; template <int EPI, bool SWP> ...
;     ...
;   float ss_next = 0.f;
;   if (has_next && e.nss > 0 && tid < 256)
;     for (int i = 0; i < e.nss; ++i) ss_next += e.ss[(size_t)(brow_n + tid) * e.nss + i];
.LBB0_79:
	v_add_u32_e32 v0, s15, v218
	v_ashrrev_i32_e32 v1, 31, v0
	v_lshl_add_u64 v[0:1], v[0:1], 2, s[0:1]
	global_load_dword v240, v[0:1], off

; #define STAGE_AX(AG, b, h, kt) do { _Pragma("unroll") for (int i = 0; i < 2; ++i)                                    \
;       __builtin_amdgcn_global_load_lds((const unsigned*)(((AG) + ((size_t)(kt) * (BK * 2) + (size_t)((h) * 2 + i) * 128 * lda)) + aoff), \
;                                        (unsigned*)(shm + SLOTA(b, h) + wid * 1024 + i * 8192), 16, 0, 0); } while (0)
; #define STAGE_BX(BG, b, h, kt) do { _Pragma("unroll") for (int i = 0; i < 2; ++i)                                    \
;       __builtin_amdgcn_global_load_lds((const unsigned*)(((BG) + ((size_t)(kt) * (BK * 2) + (size_t)((h) * 2 + i) * 128 * K)) + boff),   \
;                                        (unsigned*)(shm + SLOTB(b, h) + wid * 1024 + i * 8192), 16, 0, 0); } while (0)
; template <int EPI, bool SWP> ...
;     ...
;   if (has_next) {
;     STAGE_BX(Bg_n, 1, 0, 1); STAGE_AX(Ag_n, 1, 0, 1); STAGE_BX(Bg_n, 1, 1, 1);
;     if (e.nss > 0 && tid < 256) s_rstd_n[tid] = rsqrtf(ss_next * (1.f / DM) + 1e-6f);
;   }
.LBB0_86:
	s_andn2_b64 vcc, exec, s[70:71]
	s_cbranch_vccnz .LBB0_73
	s_mov_b32 m0, s83
	v_lshl_add_u64 v[128:129], v[212:213], 0, s[28:29]
	global_load_lds_dwordx4 v[128:129], off
	v_lshl_add_u64 v[128:129], v[212:213], 0, s[34:35]
	s_mov_b32 m0, s66
	s_nop 0
	global_load_lds_dwordx4 v[128:129], off
	v_lshl_add_u64 v[128:129], v[214:215], 0, s[28:29]
	s_mov_b32 m0, s84
	s_nop 0
	global_load_lds_dwordx4 v[128:129], off
	v_lshl_add_u64 v[128:129], v[214:215], 0, s[34:35]
	s_mov_b32 m0, s67
	s_nop 0
	global_load_lds_dwordx4 v[128:129], off
	v_lshl_add_u64 v[128:129], v[212:213], 0, s[44:45]
	s_mov_b32 m0, s85
	s_nop 0
	global_load_lds_dwordx4 v[128:129], off
	v_lshl_add_u64 v[128:129], v[212:213], 0, s[48:49]
	s_mov_b32 m0, s78
	s_nop 0
	global_load_lds_dwordx4 v[128:129], off
	s_and_saveexec_b64 s[70:71], s[6:7]
	s_cbranch_execz .LBB0_72
	v_add_f32_e32 v240, 0, v240
	v_fmamk_f32 v235, v240, 0x3a000000, v233
	v_cmp_gt_f32_e32 vcc, s18, v235
	v_mul_f32_e32 v128, 0x4b800000, v235
	s_xor_b32 s15, s69, 0x100
	v_cndmask_b32_e32 v128, v235, v128, vcc
	v_rsq_f32_e32 v128, v128
	s_nop 0
	v_mul_f32_e32 v129, 0x45800000, v128
	v_cndmask_b32_e32 v128, v128, v129, vcc
	v_lshl_add_u32 v129, s15, 2, v227
	ds_write_b32 v129, v128
	s_branch .LBB0_72

; template <int EPI, bool SWP> ...
;     ...
;   float ss_next = 0.f;
;   if (has_next && e.nss > 0 && tid < 256)
;     for (int i = 0; i < e.nss; ++i) ss_next += e.ss[(size_t)(brow_n + tid) * e.nss + i];
.LBB0_194:
	v_readlane_b32 s6, v254, 58
	v_readlane_b32 s7, v254, 59
	s_nor_b64 s[12:13], s[6:7], s[26:27]
	v_mov_b32_e32 v198, 0x358637bd
	s_and_saveexec_b64 s[6:7], s[12:13]
	s_cbranch_execz .LBB0_196
	v_add_u32_e32 v0, s31, v202
	v_ashrrev_i32_e32 v1, 31, v0
	v_readlane_b32 s12, v254, 50
	v_lshlrev_b64 v[0:1], 5, v[0:1]
	v_readlane_b32 s13, v254, 51
	s_nop 1
	v_lshl_add_u64 v[4:5], s[12:13], 0, v[0:1]
	global_load_dwordx4 v[240:243], v[4:5], off
	s_nop 0
	global_load_dwordx4 v[244:247], v[4:5], off offset:16

; #define STAGE_AX(AG, b, h, kt) do { _Pragma("unroll") for (int i = 0; i < 2; ++i)                                    \
;       __builtin_amdgcn_global_load_lds((const unsigned*)(((AG) + ((size_t)(kt) * (BK * 2) + (size_t)((h) * 2 + i) * 128 * lda)) + aoff), \
;                                        (unsigned*)(shm + SLOTA(b, h) + wid * 1024 + i * 8192), 16, 0, 0); } while (0)
; #define STAGE_BX(BG, b, h, kt) do { _Pragma("unroll") for (int i = 0; i < 2; ++i)                                    \
;       __builtin_amdgcn_global_load_lds((const unsigned*)(((BG) + ((size_t)(kt) * (BK * 2) + (size_t)((h) * 2 + i) * 128 * K)) + boff),   \
;                                        (unsigned*)(shm + SLOTB(b, h) + wid * 1024 + i * 8192), 16, 0, 0); } while (0)
; template <int EPI, bool SWP> ...
;     ...
;   if (has_next) {
;     STAGE_BX(Bg_n, 1, 0, 1); STAGE_AX(Ag_n, 1, 0, 1); STAGE_BX(Bg_n, 1, 1, 1);
;     if (e.nss > 0 && tid < 256) s_rstd_n[tid] = rsqrtf(ss_next * (1.f / DM) + 1e-6f);
;   }
.LBB0_202:
	s_andn2_b64 vcc, exec, s[70:71]
	s_cbranch_vccnz .LBB0_206
	v_lshl_add_u64 v[128:129], s[74:75], 0, v[192:193]
	s_mov_b64 s[6:7], 0x80
	s_mov_b32 m0, s25
	v_lshl_add_u64 v[130:131], v[128:129], 0, s[6:7]
	s_mov_b64 s[12:13], 0x40080
	global_load_lds_dwordx4 v[130:131], off
	v_lshl_add_u64 v[130:131], v[128:129], 0, s[12:13]
	s_mov_b32 m0, s66
	s_nop 0
	global_load_lds_dwordx4 v[130:131], off
	v_lshl_add_u64 v[130:131], s[72:73], 0, v[192:193]
	v_lshl_add_u64 v[132:133], v[130:131], 0, s[6:7]
	s_mov_b32 m0, s48
	v_lshl_add_u64 v[130:131], v[130:131], 0, s[12:13]
	global_load_lds_dwordx4 v[132:133], off
	s_mov_b32 m0, s67
	s_nop 0
	global_load_lds_dwordx4 v[130:131], off
	v_lshl_add_u64 v[130:131], v[128:129], 0, s[80:81]
	s_mov_b32 m0, s49
	v_lshl_add_u64 v[128:129], v[128:129], 0, s[82:83]
	global_load_lds_dwordx4 v[130:131], off
	s_mov_b32 m0, s16
	s_nop 0
	global_load_lds_dwordx4 v[128:129], off
	s_mov_b64 s[6:7], exec
	v_readlane_b32 s12, v254, 60
	v_readlane_b32 s13, v254, 61
	s_and_b64 s[12:13], s[6:7], s[12:13]
	s_mov_b64 exec, s[12:13]
	s_cbranch_execz .LBB0_205
	s_mov_b32 s9, 0x800000
	v_add_f32_e32 v240, 0, v240
	v_add_f32_e32 v240, v240, v241
	v_add_f32_e32 v240, v240, v242
	v_add_f32_e32 v240, v240, v243
	v_add_f32_e32 v240, v240, v244
	v_add_f32_e32 v240, v240, v245
	v_add_f32_e32 v240, v240, v246
	v_add_f32_e32 v240, v240, v247
	v_fmamk_f32 v198, v240, 0x3a000000, v223
	v_mul_f32_e32 v128, 0x4b800000, v198
	v_cmp_gt_f32_e32 vcc, s9, v198
	v_readlane_b32 s9, v255, 2
	s_nop 0
	v_cndmask_b32_e32 v128, v198, v128, vcc
	v_rsq_f32_e32 v128, v128
	s_nop 0
	v_mul_f32_e32 v129, 0x45800000, v128
	v_cndmask_b32_e32 v128, v128, v129, vcc
	v_lshl_add_u32 v129, s9, 2, v211
	ds_write_b32 v129, v128

; template <int EPI, bool SWP> ...
;     ...
;   float ss_next = 0.f;
;   if (has_next && e.nss > 0 && tid < 256)
;     for (int i = 0; i < e.nss; ++i) ss_next += e.ss[(size_t)(brow_n + tid) * e.nss + i];
.LBB0_266:
	v_readlane_b32 s6, v254, 58
	v_readlane_b32 s7, v254, 59
	s_nor_b64 s[8:9], s[6:7], s[26:27]
	v_mov_b32_e32 v224, 0x358637bd
	s_and_saveexec_b64 s[6:7], s[8:9]
	s_cbranch_execz .LBB0_268
	v_add_u32_e32 v0, s31, v202
	v_ashrrev_i32_e32 v1, 31, v0
	v_readlane_b32 s8, v254, 50
	v_lshlrev_b64 v[0:1], 5, v[0:1]
	v_readlane_b32 s9, v254, 51
	s_nop 1
	v_lshl_add_u64 v[4:5], s[8:9], 0, v[0:1]
	global_load_dwordx4 v[240:243], v[4:5], off
	s_nop 0
	global_load_dwordx4 v[244:247], v[4:5], off offset:16

; #define STAGE_AX(AG, b, h, kt) do { _Pragma("unroll") for (int i = 0; i < 2; ++i)                                    \
;       __builtin_amdgcn_global_load_lds((const unsigned*)(((AG) + ((size_t)(kt) * (BK * 2) + (size_t)((h) * 2 + i) * 128 * lda)) + aoff), \
;                                        (unsigned*)(shm + SLOTA(b, h) + wid * 1024 + i * 8192), 16, 0, 0); } while (0)
; #define STAGE_BX(BG, b, h, kt) do { _Pragma("unroll") for (int i = 0; i < 2; ++i)                                    \
;       __builtin_amdgcn_global_load_lds((const unsigned*)(((BG) + ((size_t)(kt) * (BK * 2) + (size_t)((h) * 2 + i) * 128 * K)) + boff),   \
;                                        (unsigned*)(shm + SLOTB(b, h) + wid * 1024 + i * 8192), 16, 0, 0); } while (0)
; template <int EPI, bool SWP> ...
;     ...
;   if (has_next) {
;     STAGE_BX(Bg_n, 1, 0, 1); STAGE_AX(Ag_n, 1, 0, 1); STAGE_BX(Bg_n, 1, 1, 1);
;     if (e.nss > 0 && tid < 256) s_rstd_n[tid] = rsqrtf(ss_next * (1.f / DM) + 1e-6f);
;   }
.LBB0_274:
	s_andn2_b64 vcc, exec, s[70:71]
	s_cbranch_vccnz .LBB0_179
	s_mov_b64 s[6:7], 0x80
	s_mov_b32 m0, s12
	v_lshl_add_u64 v[128:129], v[198:199], 0, s[6:7]
	s_mov_b64 s[8:9], 0x40080
	global_load_lds_dwordx4 v[128:129], off
	v_lshl_add_u64 v[128:129], v[198:199], 0, s[8:9]
	s_mov_b32 m0, s66
	s_nop 0
	global_load_lds_dwordx4 v[128:129], off
	v_lshl_add_u64 v[128:129], v[200:201], 0, s[6:7]
	s_mov_b32 m0, s23
	s_nop 0
	global_load_lds_dwordx4 v[128:129], off
	v_lshl_add_u64 v[128:129], v[200:201], 0, s[8:9]
	s_mov_b32 m0, s67
	s_nop 0
	global_load_lds_dwordx4 v[128:129], off
	v_lshl_add_u64 v[128:129], v[198:199], 0, s[80:81]
	s_mov_b32 m0, s25
	s_nop 0
	global_load_lds_dwordx4 v[128:129], off
	v_lshl_add_u64 v[128:129], v[198:199], 0, s[82:83]
	s_mov_b32 m0, s16
	s_nop 0
	global_load_lds_dwordx4 v[128:129], off
	s_mov_b64 s[6:7], exec
	v_readlane_b32 s8, v254, 60
	v_readlane_b32 s9, v254, 61
	s_and_b64 s[8:9], s[6:7], s[8:9]
	s_mov_b64 exec, s[8:9]
	s_cbranch_execz .LBB0_178
	s_mov_b32 s8, 0x800000
	v_add_f32_e32 v240, 0, v240
	v_add_f32_e32 v240, v240, v241
	v_add_f32_e32 v240, v240, v242
	v_add_f32_e32 v240, v240, v243
	v_add_f32_e32 v240, v240, v244
	v_add_f32_e32 v240, v240, v245
	v_add_f32_e32 v240, v240, v246
	v_add_f32_e32 v240, v240, v247
	v_fmamk_f32 v224, v240, 0x3a000000, v223
	v_mul_f32_e32 v128, 0x4b800000, v224
	v_cmp_gt_f32_e32 vcc, s8, v224
	v_readlane_b32 s8, v255, 2
	s_nop 0
	v_cndmask_b32_e32 v128, v224, v128, vcc
	v_rsq_f32_e32 v128, v128
	s_nop 0
	v_mul_f32_e32 v129, 0x45800000, v128
	v_cndmask_b32_e32 v128, v128, v129, vcc
	v_lshl_add_u32 v129, s8, 2, v211
	ds_write_b32 v129, v128
	s_branch .LBB0_178

; template <int EPI, bool SWP> ...
;     ...
;   float ss_next = 0.f;
;   if (has_next && e.nss > 0 && tid < 256)
;     for (int i = 0; i < e.nss; ++i) ss_next += e.ss[(size_t)(brow_n + tid) * e.nss + i];
.LBB0_665:
	v_add_u32_e32 v0, s1, v218
	v_ashrrev_i32_e32 v1, 31, v0
	v_lshlrev_b64 v[0:1], 5, v[0:1]
	v_lshl_add_u64 v[4:5], s[26:27], 0, v[0:1]
	global_load_dwordx4 v[240:243], v[4:5], off
	s_nop 0
	global_load_dwordx4 v[244:247], v[4:5], off offset:16

; #define STAGE_AX(AG, b, h, kt) do { _Pragma("unroll") for (int i = 0; i < 2; ++i)                                    \
;       __builtin_amdgcn_global_load_lds((const unsigned*)(((AG) + ((size_t)(kt) * (BK * 2) + (size_t)((h) * 2 + i) * 128 * lda)) + aoff), \
;                                        (unsigned*)(shm + SLOTA(b, h) + wid * 1024 + i * 8192), 16, 0, 0); } while (0)
; #define STAGE_BX(BG, b, h, kt) do { _Pragma("unroll") for (int i = 0; i < 2; ++i)                                    \
;       __builtin_amdgcn_global_load_lds((const unsigned*)(((BG) + ((size_t)(kt) * (BK * 2) + (size_t)((h) * 2 + i) * 128 * K)) + boff),   \
;                                        (unsigned*)(shm + SLOTB(b, h) + wid * 1024 + i * 8192), 16, 0, 0); } while (0)
; template <int EPI, bool SWP> ...
;     ...
;   if (has_next) {
;     STAGE_BX(Bg_n, 1, 0, 1); STAGE_AX(Ag_n, 1, 0, 1); STAGE_BX(Bg_n, 1, 1, 1);
;     if (e.nss > 0 && tid < 256) s_rstd_n[tid] = rsqrtf(ss_next * (1.f / DM) + 1e-6f);
;   }
.LBB0_672:
	s_andn2_b64 vcc, exec, s[62:63]
	s_cbranch_vccnz .LBB0_659
	s_mov_b32 m0, s82
	v_lshl_add_u64 v[128:129], v[212:213], 0, s[18:19]
	global_load_lds_dwordx4 v[128:129], off
	v_lshl_add_u64 v[128:129], v[212:213], 0, s[20:21]
	s_mov_b32 m0, s83
	s_nop 0
	global_load_lds_dwordx4 v[128:129], off
	v_lshl_add_u64 v[128:129], v[214:215], 0, s[18:19]
	s_mov_b32 m0, s84
	s_nop 0
	global_load_lds_dwordx4 v[128:129], off
	v_lshl_add_u64 v[128:129], v[214:215], 0, s[20:21]
	s_mov_b32 m0, s85
	s_nop 0
	global_load_lds_dwordx4 v[128:129], off
	v_lshl_add_u64 v[128:129], v[212:213], 0, s[28:29]
	s_mov_b32 m0, s70
	s_nop 0
	global_load_lds_dwordx4 v[128:129], off
	v_lshl_add_u64 v[128:129], v[212:213], 0, s[34:35]
	s_mov_b32 m0, s86
	s_nop 0
	global_load_lds_dwordx4 v[128:129], off
	s_and_saveexec_b64 s[62:63], s[8:9]
	s_cbranch_execz .LBB0_658
	v_add_f32_e32 v240, 0, v240
	v_add_f32_e32 v240, v240, v241
	v_add_f32_e32 v240, v240, v242
	v_add_f32_e32 v240, v240, v243
	v_add_f32_e32 v240, v240, v244
	v_add_f32_e32 v240, v240, v245
	v_add_f32_e32 v240, v240, v246
	v_add_f32_e32 v240, v240, v247
	v_fmamk_f32 v235, v240, 0x3a000000, v233
	v_mul_f32_e32 v128, 0x4b800000, v235
	v_cmp_gt_f32_e32 vcc, s74, v235
	s_xor_b32 s1, s61, 0x100
	s_nop 0
	v_cndmask_b32_e32 v128, v235, v128, vcc
	v_rsq_f32_e32 v128, v128
	s_nop 0
	v_mul_f32_e32 v129, 0x45800000, v128
	v_cndmask_b32_e32 v128, v128, v129, vcc
	v_lshl_add_u32 v129, s1, 2, v227
	ds_write_b32 v129, v128
	s_branch .LBB0_658
